# v31 + 188 s_nop after P1 so every K-loop keeps the byte offset it had in v29 (tests whether loop placement explains the v31 regression)
# speedup vs baseline: 1.0023x; 1.0021x over previous
.LBB0_143:
	s_nop 0
	s_nop 0
	s_nop 0
	s_nop 0
	s_nop 0
	s_nop 0
	s_nop 0
	s_nop 0
	s_nop 0
	s_nop 0
	s_nop 0
	s_nop 0
	s_nop 0
	s_nop 0
	s_nop 0
	s_nop 0
	s_nop 0
	s_nop 0
	s_nop 0
	s_nop 0
	s_nop 0
	s_nop 0
	s_nop 0
	s_nop 0
	s_nop 0
	s_nop 0
	s_nop 0
	s_nop 0
	s_nop 0
	s_nop 0
	s_nop 0
	s_nop 0
	s_nop 0
	s_nop 0
	s_nop 0
	s_nop 0
	s_nop 0
	s_nop 0
	s_nop 0
	s_nop 0
	s_nop 0
	s_nop 0
	s_nop 0
	s_nop 0
	s_nop 0
	s_nop 0
	s_nop 0
	s_nop 0
	s_nop 0
	s_nop 0
	s_nop 0
	s_nop 0
	s_nop 0
	s_nop 0
	s_nop 0
	s_nop 0
	s_nop 0
	s_nop 0
	s_nop 0
	s_nop 0
	s_nop 0
	s_nop 0
	s_nop 0
	s_nop 0
	s_nop 0
	s_nop 0
	s_nop 0
	s_nop 0
	s_nop 0
	s_nop 0
	s_nop 0
	s_nop 0
	s_nop 0
	s_nop 0
	s_nop 0
	s_nop 0
	s_nop 0
	s_nop 0
	s_nop 0
	s_nop 0
	s_nop 0
	s_nop 0
	s_nop 0
	s_nop 0
	s_nop 0
	s_nop 0
	s_nop 0
	s_nop 0
	s_nop 0
	s_nop 0
	s_nop 0
	s_nop 0
	s_nop 0
	s_nop 0
	s_nop 0
	s_nop 0
	s_nop 0
	s_nop 0
	s_nop 0
	s_nop 0
	s_nop 0
	s_nop 0
	s_nop 0
	s_nop 0
	s_nop 0
	s_nop 0
	s_nop 0
	s_nop 0
	s_nop 0
	s_nop 0
	s_nop 0
	s_nop 0
	s_nop 0
	s_nop 0
	s_nop 0
	s_nop 0
	s_nop 0
	s_nop 0
	s_nop 0
	s_nop 0
	s_nop 0
	s_nop 0
	s_nop 0
	s_nop 0
	s_nop 0
	s_nop 0
	s_nop 0
	s_nop 0
	s_nop 0
	s_nop 0
	s_nop 0
	s_nop 0
	s_nop 0
	s_nop 0
	s_nop 0
	s_nop 0
	s_nop 0
	s_nop 0
	s_nop 0
	s_nop 0
	s_nop 0
	s_nop 0
	s_nop 0
	s_nop 0
	s_nop 0
	s_nop 0
	s_nop 0
	s_nop 0
	s_nop 0
	s_nop 0
	s_nop 0
	s_nop 0
	s_nop 0
	s_nop 0
	s_nop 0
	s_nop 0
	s_nop 0
	s_nop 0
	s_nop 0
	s_nop 0
	s_nop 0
	s_nop 0
	s_nop 0
	s_nop 0
	s_nop 0
	s_nop 0
	s_nop 0
	s_nop 0
	s_nop 0
	s_nop 0
	s_nop 0
	s_nop 0
	s_nop 0
	s_nop 0
	s_nop 0
	s_nop 0
	s_nop 0
	s_nop 0
	s_nop 0
	s_nop 0
	s_nop 0
	s_nop 0
	s_nop 0
	s_nop 0
	s_nop 0
	s_nop 0
	s_nop 0
	s_nop 0
	s_cmp_lt_u32 s61, 3
	s_cbranch_scc1 .LBB0_197
	s_waitcnt vmcnt(0)
	v_cmp_eq_u32_e32 vcc, 0, v0
	s_waitcnt lgkmcnt(0)
	s_barrier
	s_and_saveexec_b64 s[4:5], vcc
	s_cbranch_execz .LBB0_196
	v_readlane_b32 s26, v255, 2
	v_mov_b32_e32 v1, s91
	s_waitcnt vmcnt(0) expcnt(0) lgkmcnt(0)
	ds_read_b32 v3, v1
	ds_read_b32 v1, v1 offset:4
	s_waitcnt lgkmcnt(1)
	v_cmp_ne_u32_e32 vcc, 0, v3
	s_cbranch_vccnz .LBB0_160
	v_readlane_b32 s6, v255, 0
	v_readlane_b32 s7, v255, 1
	s_load_dwordx2 s[10:11], s[6:7], 0x4
	s_lshl_b64 s[6:7], s[12:13], 2
	s_add_u32 s6, s24, s6
	s_addc_u32 s7, s25, s7
	s_add_u32 s8, s6, 0x1000
	s_addc_u32 s9, s7, 0
	s_waitcnt lgkmcnt(0)
	s_mul_i32 s27, s10, s85
	s_add_u32 s10, s6, 0x1100
	s_mul_i32 s27, s27, s11
	s_addc_u32 s11, s7, 0
	s_add_u32 s14, s6, 0x1200
	s_addc_u32 s15, s7, 0
	s_add_u32 s16, s6, 0x1300
	s_addc_u32 s17, s7, 0
	s_mov_b32 s28, 1
	v_mov_b32_e32 v17, 0
	s_branch .LBB0_148
